# attn dense loops: Q-load vmcnt waits hoisted out of the loop, counted vmcnt at the K/V LDS staging (original position)
# baseline (speedup 1.0000x reference)
; #define MFMA(a, b, c) __builtin_amdgcn_mfma_f32_32x32x16_bf16((a), (b), (c), 0, 0, 0)
; template <int DQK, bool BAND, int QT> ...
;     ...
;       f32x16 s[2][QT];
; #pragma unroll
;       for (int a = 0; a < 2; ++a)
; #pragma unroll
;         for (int b = 0; b < QT; ++b)
; #pragma unroll
;           for (int r = 0; r < 16; ++r) s[a][b][r] = 0.f;
; #pragma unroll
;       for (int ks = 0; ks < NKS; ++ks) {
;         const bf16x8 k0 = *(const bf16x8*)(st + k_rd + ks * 32);
;         const bf16x8 k1 = *(const bf16x8*)(st + k_rd + 32 * KROW + ks * 32);
; #pragma unroll
;         for (int qt = 0; qt < QT; ++qt) {
;           s[0][qt] = MFMA(k0, qf[qt][ks], s[0][qt]);
;           s[1][qt] = MFMA(k1, qf[qt][ks], s[1][qt]);
;         }
;       }
;       __builtin_amdgcn_s_setprio(3);
;       bf16x8 pf[QT][4];
;       const float cc = BAND ? 1.0f : scale_log2;
;       const float th = BAND ? 8.0f : 8.0f / scale_log2;
; #pragma unroll
;       for (int qt = 0; qt < QT; ++qt) {
;         if (BAND) {
; #pragma unroll
;           for (int a = 0; a < 2; ++a)
; #pragma unroll
;             for (int r = 0; r < 16; ++r) {
;               const int kidx = kt + 32 * a + (r & 7) + 8 * h + 16 * (r >> 3);
;               const int rel = kidx - (qw0 + qt * 32 + ql);
;               const bool ok = (rel >= -64) && (rel <= 64);
;               const int bi = ok ? rel + 64 : 0;
;               s[a][qt][r] = ok ? fmaf(s[a][qt][r], scale_log2, bias_l[bi]) : -1e30f;
;             }
;         }
;         float mx = s[0][qt][0];
; #pragma unroll
;         for (int r = 1; r < 16; ++r) mx = fmaxf(mx, s[0][qt][r]);
; #pragma unroll
;         for (int r = 0; r < 16; ++r) mx = fmaxf(mx, s[1][qt][r]);
;         mx = fmaxf(mx, __shfl_xor(mx, 32));
;         if (__builtin_amdgcn_ballot_w64(mx > m[qt] + th) != 0) {
;           const float mn = fmaxf(m[qt], mx);
;           const float alpha = __builtin_amdgcn_exp2f((m[qt] - mn) * cc);
;           m[qt] = mn;
;           l[qt] *= alpha;
; #pragma unroll
;           for (int r = 0; r < 16; ++r) { o[0][qt][r] *= alpha; o[1][qt][r] *= alpha; }
;         }
.LBB0_831:
	s_bitcmp1_b32 s1, 0
	s_cselect_b32 s7, 0x4800, 0
	s_add_i32 s7, s7, 0
	v_add3_u32 v203, s7, v185, v0
	ds_read_b128 v[98:101], v203 offset:4608
	ds_read_b128 v[102:105], v203
	ds_read_b128 v[206:209], v203 offset:32
	ds_read_b128 v[210:213], v203 offset:4640
	s_waitcnt lgkmcnt(3)
	v_mfma_f32_32x32x16_bf16 v[66:81], v[98:101], v[146:149], 0
	s_waitcnt lgkmcnt(2)
	v_mfma_f32_32x32x16_bf16 v[82:97], v[102:105], v[146:149], 0
	v_mfma_f32_32x32x16_bf16 v[114:129], v[102:105], v[162:165], 0
	v_mfma_f32_32x32x16_bf16 v[98:113], v[98:101], v[162:165], 0
	s_waitcnt lgkmcnt(1)
	v_mfma_f32_32x32x16_bf16 v[82:97], v[206:209], v[150:153], v[82:97]
	s_waitcnt lgkmcnt(0)
	v_mfma_f32_32x32x16_bf16 v[66:81], v[210:213], v[150:153], v[66:81]
	v_mfma_f32_32x32x16_bf16 v[114:129], v[206:209], v[166:169], v[114:129]
	v_mfma_f32_32x32x16_bf16 v[98:113], v[210:213], v[166:169], v[98:113]
	ds_read_b128 v[206:209], v203 offset:64
	ds_read_b128 v[210:213], v203 offset:4672
	s_waitcnt lgkmcnt(1)
	v_mfma_f32_32x32x16_bf16 v[82:97], v[206:209], v[154:157], v[82:97]
	s_waitcnt lgkmcnt(0)
	v_mfma_f32_32x32x16_bf16 v[66:81], v[210:213], v[154:157], v[66:81]
	v_mfma_f32_32x32x16_bf16 v[114:129], v[206:209], v[170:173], v[114:129]
	v_mfma_f32_32x32x16_bf16 v[98:113], v[210:213], v[170:173], v[98:113]
	ds_read_b128 v[206:209], v203 offset:96
	ds_read_b128 v[210:213], v203 offset:4704
	s_waitcnt lgkmcnt(1)
	v_mfma_f32_32x32x16_bf16 v[82:97], v[206:209], v[158:161], v[82:97]
	s_waitcnt lgkmcnt(0)
	v_mfma_f32_32x32x16_bf16 v[66:81], v[210:213], v[158:161], v[66:81]
	v_mfma_f32_32x32x16_bf16 v[114:129], v[206:209], v[174:177], v[114:129]
	v_mfma_f32_32x32x16_bf16 v[98:113], v[210:213], v[174:177], v[98:113]
	s_setprio 3
	s_nop 6
	v_max_f32_e32 v203, v83, v83
	v_max_f32_e32 v204, v82, v82
	v_max_f32_e32 v203, v204, v203
	v_max3_f32 v203, v203, v84, v85
	v_max3_f32 v203, v203, v86, v87
	v_max3_f32 v203, v203, v88, v89
	v_max3_f32 v203, v203, v90, v91
	v_max3_f32 v203, v203, v92, v93
	v_max3_f32 v203, v203, v94, v95
	v_max3_f32 v203, v203, v96, v97
	v_max3_f32 v203, v203, v66, v67
	v_max3_f32 v203, v203, v68, v69
	v_max3_f32 v203, v203, v70, v71
	v_max3_f32 v203, v203, v72, v73
	v_max3_f32 v203, v203, v74, v75
	v_max3_f32 v203, v203, v76, v77
	v_max3_f32 v203, v203, v78, v79
	v_max3_f32 v203, v203, v80, v81
	ds_bpermute_b32 v204, v179, v203
	s_waitcnt lgkmcnt(0)
	v_max_f32_e32 v204, v204, v204
	v_max_f32_e32 v203, v203, v204
	v_add_f32_e32 v204, 0x42317218, v197
	v_cmp_gt_f32_e32 vcc, v203, v204
	s_cbranch_vccz .LBB0_833
	v_max_f32_e32 v203, v203, v203
	v_max_f32_e32 v204, v197, v197
	v_max_f32_e32 v203, v204, v203
	v_sub_f32_e32 v197, v197, v203
	v_mul_f32_e32 v197, 0x3e38aa3b, v197
	v_exp_f32_e32 v204, v197
	v_mov_b32_e32 v197, v203
	v_mul_f32_e32 v187, v187, v204
	v_pk_mul_f32 v[64:65], v[64:65], v[204:205] op_sel_hi:[1,0]
	v_pk_mul_f32 v[62:63], v[62:63], v[204:205] op_sel_hi:[1,0]
	v_pk_mul_f32 v[60:61], v[60:61], v[204:205] op_sel_hi:[1,0]
	v_pk_mul_f32 v[58:59], v[58:59], v[204:205] op_sel_hi:[1,0]
	v_pk_mul_f32 v[56:57], v[56:57], v[204:205] op_sel_hi:[1,0]
	v_pk_mul_f32 v[54:55], v[54:55], v[204:205] op_sel_hi:[1,0]
	v_pk_mul_f32 v[52:53], v[52:53], v[204:205] op_sel_hi:[1,0]
	v_pk_mul_f32 v[50:51], v[50:51], v[204:205] op_sel_hi:[1,0]
	v_pk_mul_f32 v[48:49], v[48:49], v[204:205] op_sel_hi:[1,0]
	v_pk_mul_f32 v[46:47], v[46:47], v[204:205] op_sel_hi:[1,0]
	v_pk_mul_f32 v[44:45], v[44:45], v[204:205] op_sel_hi:[1,0]
	v_pk_mul_f32 v[42:43], v[42:43], v[204:205] op_sel_hi:[1,0]
	v_pk_mul_f32 v[40:41], v[40:41], v[204:205] op_sel_hi:[1,0]
	v_pk_mul_f32 v[38:39], v[38:39], v[204:205] op_sel_hi:[1,0]
	v_pk_mul_f32 v[36:37], v[36:37], v[204:205] op_sel_hi:[1,0]
	v_pk_mul_f32 v[34:35], v[34:35], v[204:205] op_sel_hi:[1,0]

; template <int DQK, bool BAND, int QT> ...
;     ...
;   auto lstore = [&](char* st) {
; #pragma unroll
;     for (int i = 0; i < NKL; ++i) *(u32x4*)(st + klds[i]) = rk[i];
; #pragma unroll
;     for (int i = 0; i < 2; ++i) *(u32x4*)(st + vlds0 + i * 32 * LROW) = rv[i];
;   };
;     ...
;       __builtin_amdgcn_s_setprio(0);
;       if (more) lstore(lds + ((it + 1) & 1) * ST);
.LBB0_835:
	s_setprio 0
	s_andn2_b64 vcc, exec, s[2:3]
	s_cbranch_vccnz .LBB0_828
	s_andn2_b32 s2, 1, s1
	s_mulk_i32 s2, 0x4800
	s_add_i32 s2, s2, 0
	v_add_u32_e32 v203, s2, v184
	s_waitcnt vmcnt(3)
	ds_write_b128 v203, v[130:133]
	v_add_u32_e32 v203, s2, v186
	s_waitcnt vmcnt(2)
	ds_write_b128 v203, v[134:137]
	v_add_u32_e32 v203, s2, v182
	s_waitcnt vmcnt(1)
	ds_write_b128 v203, v[138:141] offset:9216
	s_waitcnt vmcnt(0)
	ds_write_b128 v203, v[142:145] offset:13824
	s_branch .LBB0_828

; #define MFMA(a, b, c) __builtin_amdgcn_mfma_f32_32x32x16_bf16((a), (b), (c), 0, 0, 0)
; template <int DQK, bool BAND, int QT> ...
;     ...
;       f32x16 s[2][QT];
; #pragma unroll
;       for (int a = 0; a < 2; ++a)
; #pragma unroll
;         for (int b = 0; b < QT; ++b)
; #pragma unroll
;           for (int r = 0; r < 16; ++r) s[a][b][r] = 0.f;
; #pragma unroll
;       for (int ks = 0; ks < NKS; ++ks) {
;         const bf16x8 k0 = *(const bf16x8*)(st + k_rd + ks * 32);
;         const bf16x8 k1 = *(const bf16x8*)(st + k_rd + 32 * KROW + ks * 32);
; #pragma unroll
;         for (int qt = 0; qt < QT; ++qt) {
;           s[0][qt] = MFMA(k0, qf[qt][ks], s[0][qt]);
;           s[1][qt] = MFMA(k1, qf[qt][ks], s[1][qt]);
;         }
;       }
;       __builtin_amdgcn_s_setprio(3);
;       bf16x8 pf[QT][4];
;       const float cc = BAND ? 1.0f : scale_log2;
;       const float th = BAND ? 8.0f : 8.0f / scale_log2;
; #pragma unroll
;       for (int qt = 0; qt < QT; ++qt) {
;         if (BAND) {
; #pragma unroll
;           for (int a = 0; a < 2; ++a)
; #pragma unroll
;             for (int r = 0; r < 16; ++r) {
;               const int kidx = kt + 32 * a + (r & 7) + 8 * h + 16 * (r >> 3);
;               const int rel = kidx - (qw0 + qt * 32 + ql);
;               const bool ok = (rel >= -64) && (rel <= 64);
;               const int bi = ok ? rel + 64 : 0;
;               s[a][qt][r] = ok ? fmaf(s[a][qt][r], scale_log2, bias_l[bi]) : -1e30f;
;             }
;         }
;         float mx = s[0][qt][0];
; #pragma unroll
;         for (int r = 1; r < 16; ++r) mx = fmaxf(mx, s[0][qt][r]);
; #pragma unroll
;         for (int r = 0; r < 16; ++r) mx = fmaxf(mx, s[1][qt][r]);
;         mx = fmaxf(mx, __shfl_xor(mx, 32));
;         if (__builtin_amdgcn_ballot_w64(mx > m[qt] + th) != 0) {
;           const float mn = fmaxf(m[qt], mx);
;           const float alpha = __builtin_amdgcn_exp2f((m[qt] - mn) * cc);
;           m[qt] = mn;
;           l[qt] *= alpha;
; #pragma unroll
;           for (int r = 0; r < 16; ++r) { o[0][qt][r] *= alpha; o[1][qt][r] *= alpha; }
;         }
.LBB0_844:
	s_bitcmp1_b32 s1, 0
	s_cselect_b32 s7, 0x5800, 0
	s_add_i32 s7, s7, 0
	v_add3_u32 v239, s7, v235, v0
	ds_read_b128 v[98:101], v239 offset:6656
	ds_read_b128 v[102:105], v239
	ds_read_b128 v[240:243], v239 offset:32
	ds_read_b128 v[244:247], v239 offset:6688
	s_waitcnt lgkmcnt(3)
	v_mfma_f32_32x32x16_bf16 v[66:81], v[98:101], v[142:145], 0
	s_waitcnt lgkmcnt(2)
	v_mfma_f32_32x32x16_bf16 v[82:97], v[102:105], v[142:145], 0
	v_mfma_f32_32x32x16_bf16 v[114:129], v[102:105], v[174:177], 0
	v_mfma_f32_32x32x16_bf16 v[98:113], v[98:101], v[174:177], 0
	s_waitcnt lgkmcnt(1)
	v_mfma_f32_32x32x16_bf16 v[82:97], v[240:243], v[150:153], v[82:97]
	s_waitcnt lgkmcnt(0)
	v_mfma_f32_32x32x16_bf16 v[66:81], v[244:247], v[150:153], v[66:81]
	v_mfma_f32_32x32x16_bf16 v[114:129], v[240:243], v[178:181], v[114:129]
	v_mfma_f32_32x32x16_bf16 v[98:113], v[244:247], v[178:181], v[98:113]
	ds_read_b128 v[240:243], v239 offset:64
	ds_read_b128 v[244:247], v239 offset:6720
	s_waitcnt lgkmcnt(1)
	v_mfma_f32_32x32x16_bf16 v[82:97], v[240:243], v[154:157], v[82:97]
	s_waitcnt lgkmcnt(0)
	v_mfma_f32_32x32x16_bf16 v[66:81], v[244:247], v[154:157], v[66:81]
	v_mfma_f32_32x32x16_bf16 v[114:129], v[240:243], v[182:185], v[114:129]
	v_mfma_f32_32x32x16_bf16 v[98:113], v[244:247], v[182:185], v[98:113]
	ds_read_b128 v[240:243], v239 offset:96
	ds_read_b128 v[244:247], v239 offset:6752
	s_waitcnt lgkmcnt(1)
	v_mfma_f32_32x32x16_bf16 v[82:97], v[240:243], v[158:161], v[82:97]
	s_waitcnt lgkmcnt(0)
	v_mfma_f32_32x32x16_bf16 v[66:81], v[244:247], v[158:161], v[66:81]
	v_mfma_f32_32x32x16_bf16 v[114:129], v[240:243], v[186:189], v[114:129]
	v_mfma_f32_32x32x16_bf16 v[98:113], v[244:247], v[186:189], v[98:113]
	ds_read_b128 v[240:243], v239 offset:128
	ds_read_b128 v[244:247], v239 offset:6784
	s_waitcnt lgkmcnt(1)
	v_mfma_f32_32x32x16_bf16 v[82:97], v[240:243], v[162:165], v[82:97]
	s_waitcnt lgkmcnt(0)
	v_mfma_f32_32x32x16_bf16 v[66:81], v[244:247], v[162:165], v[66:81]
	v_mfma_f32_32x32x16_bf16 v[114:129], v[240:243], v[190:193], v[114:129]
	v_mfma_f32_32x32x16_bf16 v[98:113], v[244:247], v[190:193], v[98:113]
	ds_read_b128 v[240:243], v239 offset:160
	ds_read_b128 v[244:247], v239 offset:6816
	s_waitcnt lgkmcnt(1)
	v_mfma_f32_32x32x16_bf16 v[82:97], v[240:243], v[166:169], v[82:97]
	s_waitcnt lgkmcnt(0)
	v_mfma_f32_32x32x16_bf16 v[66:81], v[244:247], v[166:169], v[66:81]
	v_mfma_f32_32x32x16_bf16 v[114:129], v[240:243], v[194:197], v[114:129]
	v_mfma_f32_32x32x16_bf16 v[98:113], v[244:247], v[194:197], v[98:113]
	s_setprio 3
	s_nop 6
	v_max_f32_e32 v239, v83, v83
	v_max_f32_e32 v240, v82, v82
	v_max_f32_e32 v239, v240, v239
	v_max3_f32 v239, v239, v84, v85
	v_max3_f32 v239, v239, v86, v87
	v_max3_f32 v239, v239, v88, v89
	v_max3_f32 v239, v239, v90, v91
	v_max3_f32 v239, v239, v92, v93
	v_max3_f32 v239, v239, v94, v95
	v_max3_f32 v239, v239, v96, v97
	v_max3_f32 v239, v239, v66, v67
	v_max3_f32 v239, v239, v68, v69
	v_max3_f32 v239, v239, v70, v71
	v_max3_f32 v239, v239, v72, v73
	v_max3_f32 v239, v239, v74, v75
	v_max3_f32 v239, v239, v76, v77
	v_max3_f32 v239, v239, v78, v79
	v_max3_f32 v239, v239, v80, v81
	ds_bpermute_b32 v240, v203, v239
	s_waitcnt lgkmcnt(0)
	v_max_f32_e32 v240, v240, v240
	v_max_f32_e32 v239, v239, v240
	v_add_f32_e32 v240, 0x4259535f, v237
	v_cmp_gt_f32_e32 vcc, v239, v240
	s_cbranch_vccz .LBB0_846
	v_max_f32_e32 v239, v239, v239
	v_max_f32_e32 v240, v237, v237
	v_max_f32_e32 v239, v240, v239
	v_sub_f32_e32 v237, v237, v239
	v_mul_f32_e32 v237, 0x3e16c740, v237
	v_exp_f32_e32 v240, v237
	v_mov_b32_e32 v237, v239
	v_mul_f32_e32 v236, v236, v240
	v_pk_mul_f32 v[64:65], v[64:65], v[240:241] op_sel_hi:[1,0]
	v_pk_mul_f32 v[62:63], v[62:63], v[240:241] op_sel_hi:[1,0]
	v_pk_mul_f32 v[60:61], v[60:61], v[240:241] op_sel_hi:[1,0]
	v_pk_mul_f32 v[58:59], v[58:59], v[240:241] op_sel_hi:[1,0]
	v_pk_mul_f32 v[56:57], v[56:57], v[240:241] op_sel_hi:[1,0]
	v_pk_mul_f32 v[54:55], v[54:55], v[240:241] op_sel_hi:[1,0]
	v_pk_mul_f32 v[52:53], v[52:53], v[240:241] op_sel_hi:[1,0]
	v_pk_mul_f32 v[50:51], v[50:51], v[240:241] op_sel_hi:[1,0]
	v_pk_mul_f32 v[48:49], v[48:49], v[240:241] op_sel_hi:[1,0]
	v_pk_mul_f32 v[46:47], v[46:47], v[240:241] op_sel_hi:[1,0]
	v_pk_mul_f32 v[44:45], v[44:45], v[240:241] op_sel_hi:[1,0]
	v_pk_mul_f32 v[42:43], v[42:43], v[240:241] op_sel_hi:[1,0]
	v_pk_mul_f32 v[40:41], v[40:41], v[240:241] op_sel_hi:[1,0]
	v_pk_mul_f32 v[38:39], v[38:39], v[240:241] op_sel_hi:[1,0]
	v_pk_mul_f32 v[36:37], v[36:37], v[240:241] op_sel_hi:[1,0]
	v_pk_mul_f32 v[34:35], v[34:35], v[240:241] op_sel_hi:[1,0]

; template <int DQK, bool BAND, int QT> ...
;     ...
;   auto lstore = [&](char* st) {
; #pragma unroll
;     for (int i = 0; i < NKL; ++i) *(u32x4*)(st + klds[i]) = rk[i];
; #pragma unroll
;     for (int i = 0; i < 2; ++i) *(u32x4*)(st + vlds0 + i * 32 * LROW) = rv[i];
;   };
;     ...
;       __builtin_amdgcn_s_setprio(0);
;       if (more) lstore(lds + ((it + 1) & 1) * ST);
.LBB0_848:
	s_setprio 0
	s_andn2_b64 vcc, exec, s[2:3]
	s_cbranch_vccnz .LBB0_841
	s_andn2_b32 s2, 1, s1
	s_mulk_i32 s2, 0x5800
	s_add_i32 s2, s2, 0
	v_add_u32_e32 v239, s2, v231
	s_waitcnt vmcnt(4)
	ds_write_b128 v239, v[130:133]
	v_add_u32_e32 v239, s2, v232
	s_waitcnt vmcnt(3)
	ds_write_b128 v239, v[134:137]
	v_add_u32_e32 v239, s2, v233
	s_waitcnt vmcnt(2)
	ds_write_b128 v239, v[138:141]
	v_add_u32_e32 v239, s2, v206
	s_waitcnt vmcnt(1)
	ds_write_b128 v239, v[146:149] offset:13312
	s_waitcnt vmcnt(0)
	ds_write_b128 v239, v[170:173] offset:17920
	s_branch .LBB0_841
